# HGRN2 output item phase B: fragment reads hoisted into spare registers, two straight-line token-block variants, counted lgkmcnt
# baseline (speedup 1.0000x reference)
.LBB0_107:
	s_mov_b32 s86, 0x800000
	s_mov_b32 s87, 0x9000
	ds_read_b128 v[90:93], v139
	ds_read_b128 v[86:89], v139 offset:32
	ds_read_b128 v[82:85], v139 offset:64
	ds_read_b128 v[78:81], v139 offset:96
	ds_read_b128 v[192:195], v135
	ds_read_b128 v[196:199], v135 offset:32
	ds_read_b128 v[200:203], v135 offset:64
	ds_read_b128 v[204:207], v135 offset:96
	s_and_b64 vcc, exec, s[72:73]
	s_cbranch_vccnz .Lhg_t1
	ds_read_b128 v[160:163], v130 offset:36864
	ds_read_b128 v[164:167], v130 offset:36896
	ds_read_b128 v[168:171], v130 offset:36928
	ds_read_b128 v[172:175], v130 offset:36960
	s_waitcnt lgkmcnt(4)
	v_mfma_f32_32x32x16_bf16 v[18:33], v[192:195], v[90:93], 0
	v_mfma_f32_32x32x16_bf16 v[18:33], v[196:199], v[86:89], v[18:33]
	v_mfma_f32_32x32x16_bf16 v[18:33], v[200:203], v[82:85], v[18:33]
	v_mfma_f32_32x32x16_bf16 v[18:33], v[204:207], v[78:81], v[18:33]
	ds_read_b64_tr_b16 v[208:209], v141 offset:27648
	ds_read_b64_tr_b16 v[210:211], v141 offset:28800
	ds_read_b64_tr_b16 v[212:213], v141 offset:29952
	ds_read_b64_tr_b16 v[214:215], v141 offset:31104
	s_waitcnt lgkmcnt(4)
	v_mfma_f32_32x32x16_bf16 v[2:17], v[160:163], v[90:93], 0
	v_mfma_f32_32x32x16_bf16 v[2:17], v[164:167], v[86:89], v[2:17]
	v_mfma_f32_32x32x16_bf16 v[2:17], v[168:171], v[82:85], v[2:17]
	v_mfma_f32_32x32x16_bf16 v[2:17], v[172:175], v[78:81], v[2:17]
	s_nop 2
	s_andn2_b64 vcc, exec, s[16:17]
	s_cbranch_vccnz .Lhg_nm0
	v_cndmask_b32_e64 v157, v18, 0, s[18:19]
	v_cndmask_b32_e64 v19, 0, v19, s[20:21]
	v_cndmask_b32_e64 v18, v157, v18, s[20:21]
	v_cndmask_b32_e64 v20, v20, 0, s[22:23]
	v_cndmask_b32_e64 v21, v21, 0, s[24:25]
	v_cndmask_b32_e64 v22, v22, 0, s[26:27]
	v_cndmask_b32_e64 v23, v23, 0, s[28:29]
	v_cndmask_b32_e64 v24, v24, 0, s[30:31]
	v_cndmask_b32_e64 v25, v25, 0, s[34:35]
	v_cndmask_b32_e64 v26, v26, 0, s[36:37]
	v_cndmask_b32_e64 v27, v27, 0, s[38:39]
	v_cndmask_b32_e64 v28, v28, 0, s[40:41]
	v_cndmask_b32_e64 v29, v29, 0, s[42:43]
	v_cndmask_b32_e64 v30, v30, 0, s[44:45]
	v_cndmask_b32_e64 v31, v31, 0, s[46:47]
	v_cndmask_b32_e64 v32, v32, 0, s[48:49]
	v_cndmask_b32_e64 v33, v33, 0, s[50:51]
.Lhg_nm0:
	v_cvt_pk_bf16_f32 v18, v18, v19
	v_cvt_pk_bf16_f32 v19, v20, v21
	v_cvt_pk_bf16_f32 v20, v22, v23
	v_cvt_pk_bf16_f32 v21, v24, v25
	s_nop 1
	s_waitcnt lgkmcnt(2)
	v_mfma_f32_32x32x16_bf16 v[2:17], v[208:211], v[18:21], v[2:17]
	v_cvt_pk_bf16_f32 v18, v26, v27
	v_cvt_pk_bf16_f32 v19, v28, v29
	v_cvt_pk_bf16_f32 v20, v30, v31
	v_cvt_pk_bf16_f32 v21, v32, v33
	s_nop 1
	s_waitcnt lgkmcnt(0)
	v_mfma_f32_32x32x16_bf16 v[2:17], v[212:215], v[18:21], v[2:17]
	s_branch .LBB0_82
.Lhg_t1:
	ds_read_b128 v[220:223], v134 offset:13824
	ds_read_b128 v[224:227], v134 offset:13856
	ds_read_b128 v[228:231], v134 offset:13888
	ds_read_b128 v[232:235], v134 offset:13920
	s_waitcnt lgkmcnt(4)
	v_mfma_f32_32x32x16_bf16 v[18:33], v[192:195], v[90:93], 0
	v_mfma_f32_32x32x16_bf16 v[18:33], v[196:199], v[86:89], v[18:33]
	v_mfma_f32_32x32x16_bf16 v[18:33], v[200:203], v[82:85], v[18:33]
	v_mfma_f32_32x32x16_bf16 v[18:33], v[204:207], v[78:81], v[18:33]
	ds_read_b128 v[160:163], v130 offset:36864
	ds_read_b128 v[164:167], v130 offset:36896
	ds_read_b128 v[168:171], v130 offset:36928
	ds_read_b128 v[172:175], v130 offset:36960
	ds_read_b128 v[176:179], v131 offset:18432
	ds_read_b128 v[180:183], v131 offset:18464
	ds_read_b128 v[184:187], v131 offset:18496
	ds_read_b128 v[188:191], v131 offset:18528
	s_waitcnt lgkmcnt(8)
	v_mfma_f32_32x32x16_bf16 v[192:207], v[220:223], v[90:93], 0
	v_mfma_f32_32x32x16_bf16 v[192:207], v[224:227], v[86:89], v[192:207]
	v_mfma_f32_32x32x16_bf16 v[192:207], v[228:231], v[82:85], v[192:207]
	v_mfma_f32_32x32x16_bf16 v[192:207], v[232:235], v[78:81], v[192:207]
	ds_read_b64_tr_b16 v[208:209], v141 offset:27648
	ds_read_b64_tr_b16 v[210:211], v141 offset:28800
	ds_read_b64_tr_b16 v[212:213], v141 offset:29952
	ds_read_b64_tr_b16 v[214:215], v141 offset:31104
	s_waitcnt lgkmcnt(4)
	v_mfma_f32_32x32x16_bf16 v[2:17], v[160:163], v[176:179], 0
	v_mfma_f32_32x32x16_bf16 v[2:17], v[164:167], v[180:183], v[2:17]
	v_mfma_f32_32x32x16_bf16 v[2:17], v[168:171], v[184:187], v[2:17]
	v_mfma_f32_32x32x16_bf16 v[2:17], v[172:175], v[188:191], v[2:17]
	ds_read_b64_tr_b16 v[220:221], v141 offset:32256
	ds_read_b64_tr_b16 v[222:223], v141 offset:33408
	ds_read_b64_tr_b16 v[224:225], v141 offset:34560
	ds_read_b64_tr_b16 v[226:227], v141 offset:35712
	s_andn2_b64 vcc, exec, s[16:17]
	s_cbranch_vccnz .Lhg_nm1
	v_cndmask_b32_e64 v157, v18, 0, s[18:19]
	v_cndmask_b32_e64 v19, 0, v19, s[20:21]
	v_cndmask_b32_e64 v18, v157, v18, s[20:21]
	v_cndmask_b32_e64 v20, v20, 0, s[22:23]
	v_cndmask_b32_e64 v21, v21, 0, s[24:25]
	v_cndmask_b32_e64 v22, v22, 0, s[26:27]
	v_cndmask_b32_e64 v23, v23, 0, s[28:29]
	v_cndmask_b32_e64 v24, v24, 0, s[30:31]
	v_cndmask_b32_e64 v25, v25, 0, s[34:35]
	v_cndmask_b32_e64 v26, v26, 0, s[36:37]
	v_cndmask_b32_e64 v27, v27, 0, s[38:39]
	v_cndmask_b32_e64 v28, v28, 0, s[40:41]
	v_cndmask_b32_e64 v29, v29, 0, s[42:43]
	v_cndmask_b32_e64 v30, v30, 0, s[44:45]
	v_cndmask_b32_e64 v31, v31, 0, s[46:47]
	v_cndmask_b32_e64 v32, v32, 0, s[48:49]
	v_cndmask_b32_e64 v33, v33, 0, s[50:51]
.Lhg_nm1:
	v_cvt_pk_bf16_f32 v18, v18, v19
	v_cvt_pk_bf16_f32 v19, v20, v21
	v_cvt_pk_bf16_f32 v20, v22, v23
	v_cvt_pk_bf16_f32 v21, v24, v25
	s_nop 1
	s_waitcnt lgkmcnt(6)
	v_mfma_f32_32x32x16_bf16 v[2:17], v[208:211], v[18:21], v[2:17]
	v_cvt_pk_bf16_f32 v18, v26, v27
	v_cvt_pk_bf16_f32 v19, v28, v29
	v_cvt_pk_bf16_f32 v20, v30, v31
	v_cvt_pk_bf16_f32 v21, v32, v33
	s_nop 1
	s_waitcnt lgkmcnt(4)
	v_mfma_f32_32x32x16_bf16 v[2:17], v[212:215], v[18:21], v[2:17]
	s_nop 3
	v_cndmask_b32_e64 v157, v192, 0, s[18:19]
	v_cndmask_b32_e64 v193, 0, v193, s[20:21]
	v_cndmask_b32_e64 v192, v157, v192, s[20:21]
	v_cndmask_b32_e64 v194, v194, 0, s[22:23]
	v_cndmask_b32_e64 v195, v195, 0, s[24:25]
	v_cndmask_b32_e64 v196, v196, 0, s[26:27]
	v_cndmask_b32_e64 v197, v197, 0, s[28:29]
	v_cndmask_b32_e64 v198, v198, 0, s[30:31]
	v_cndmask_b32_e64 v199, v199, 0, s[34:35]
	v_cndmask_b32_e64 v200, v200, 0, s[36:37]
	v_cndmask_b32_e64 v201, v201, 0, s[38:39]
	v_cndmask_b32_e64 v202, v202, 0, s[40:41]
	v_cndmask_b32_e64 v203, v203, 0, s[42:43]
	v_cndmask_b32_e64 v204, v204, 0, s[44:45]
	v_cndmask_b32_e64 v205, v205, 0, s[46:47]
	v_cndmask_b32_e64 v206, v206, 0, s[48:49]
	v_cndmask_b32_e64 v207, v207, 0, s[50:51]
	v_cvt_pk_bf16_f32 v18, v192, v193
	v_cvt_pk_bf16_f32 v19, v194, v195
	v_cvt_pk_bf16_f32 v20, v196, v197
	v_cvt_pk_bf16_f32 v21, v198, v199
	s_nop 1
	s_waitcnt lgkmcnt(2)
	v_mfma_f32_32x32x16_bf16 v[2:17], v[220:223], v[18:21], v[2:17]
	v_cvt_pk_bf16_f32 v18, v200, v201
	v_cvt_pk_bf16_f32 v19, v202, v203
	v_cvt_pk_bf16_f32 v20, v204, v205
	v_cvt_pk_bf16_f32 v21, v206, v207
	s_nop 1
	s_waitcnt lgkmcnt(0)
	v_mfma_f32_32x32x16_bf16 v[2:17], v[224:227], v[18:21], v[2:17]
	s_branch .LBB0_82
